# m6 plus role-aware s_setprio: hw1 scan waves raised between barrier 1 and barrier 2
# speedup vs baseline: 1.0004x; 1.0004x over previous
.LBB0_872:
	s_or_b64 exec, exec, s[52:53]
	s_waitcnt lgkmcnt(0)
	s_barrier
	s_cmp_lg_u64 s[10:11], 0
	s_cbranch_scc1 .Lmy_prio_a
	s_setprio 1
.Lmy_prio_a:
	v_add_u32_e32 v208, v182, v128
	ds_read_b128 v[116:119], v208
	s_and_saveexec_b64 s[34:35], s[14:15]
	s_xor_b64 s[52:53], exec, s[34:35]
	s_andn2_saveexec_b64 s[52:53], s[52:53]
	s_cbranch_execz .LBB0_874
	ds_read_b128 v[214:217], v184 offset:34816
	ds_read_b128 v[218:221], v184 offset:39424
	s_waitcnt lgkmcnt(1)
	v_mfma_f32_32x32x16_bf16 v[32:47], v[214:217], v[116:119], v[32:47]
	s_waitcnt lgkmcnt(0)
	v_mfma_f32_32x32x16_bf16 v[48:63], v[218:221], v[116:119], v[48:63]

.LBB0_901:
	s_or_b64 exec, exec, s[52:53]
	s_waitcnt lgkmcnt(0)
	s_barrier
	s_setprio 0
	ds_read_b128 v[32:35], v206
	ds_read_b128 v[36:39], v206 offset:16
	ds_read_b128 v[40:43], v206 offset:32
	ds_read_b128 v[44:47], v206 offset:48
	s_waitcnt lgkmcnt(3)
	v_pk_mul_f32 v[48:49], v[34:35], v[34:35]
	v_pk_mul_f32 v[50:51], v[32:33], v[32:33]
	s_nop 0
	v_pk_mov_b32 v[52:53], v[50:51], v[48:49] op_sel:[1,0]
	v_mov_b32_e32 v51, v49
	v_pk_add_f32 v[48:49], v[52:53], v[50:51]
	s_waitcnt lgkmcnt(2)
	v_pk_mul_f32 v[50:51], v[38:39], v[38:39]
	v_pk_mul_f32 v[52:53], v[36:37], v[36:37]
	v_pk_add_f32 v[48:49], v[48:49], v[48:49] op_sel:[0,1] op_sel_hi:[1,0]
	v_pk_mov_b32 v[54:55], v[52:53], v[50:51] op_sel:[1,0]
	v_mov_b32_e32 v53, v51
	v_pk_add_f32 v[50:51], v[54:55], v[52:53]
	s_waitcnt lgkmcnt(0)
	v_mul_f32_e32 v52, v44, v44
	v_mul_f32_e32 v53, v45, v45
	v_pk_add_f32 v[50:51], v[50:51], v[50:51] op_sel:[0,1] op_sel_hi:[1,0]
	v_mov_b32_e32 v49, v52
	v_mov_b32_e32 v51, v53
	v_pk_add_f32 v[48:49], v[48:49], v[50:51]
	v_mul_f32_e32 v50, v41, v41
	v_mul_f32_e32 v52, v43, v43
	v_mul_f32_e32 v54, v46, v46
	v_mul_f32_e32 v55, v47, v47
	v_pk_fma_f32 v[50:51], v[40:41], v[40:41], v[50:51] op_sel_hi:[1,1,0]
	v_pk_fma_f32 v[52:53], v[42:43], v[42:43], v[52:53] op_sel_hi:[1,1,0]
	v_mov_b32_e32 v51, v54
	v_mov_b32_e32 v53, v55
	v_pk_add_f32 v[50:51], v[50:51], v[52:53]
	s_nop 0
	v_pk_add_f32 v[48:49], v[48:49], v[50:51]
	v_and_b32_e32 v50, 64, v149
	v_add_f32_e32 v48, v48, v49
	v_xor_b32_e32 v49, 1, v149
	v_add_u32_e32 v50, 64, v50
	v_cmp_lt_i32_e32 vcc, v49, v50
	s_cmp_lt_u32 s70, 30
	s_cbranch_scc1 .Lmy_scan_w4
	s_waitcnt vmcnt(0)
	s_branch .Lmy_scan_wj
